# baseline (speedup 1.0000x reference)
; #define LAS __attribute__((address_space(3)))
; #define ATT_KRD(KOFF, DLO, DHI) do { _Pragma("unroll") for (int d0 = (DLO); d0 < (DHI); ++d0) { kf[2 * d0] = *(const LAS bf16x8*)(lds + (KOFF) + kr + 2 * d0 * KCH); kf[2 * d0 + 1] = *(const LAS bf16x8*)(lds + (KOFF) + kr + 2 * d0 * KCH + 512); } } while (0)
; #define ATT_SB() __builtin_amdgcn_sched_barrier(0)
; #define ATT_EXP2(J) do { float e0_, e1_; if ((J) < 8) { e0_ = __builtin_amdgcn_exp2f(p0[2 * (J)]); e1_ = __builtin_amdgcn_exp2f(p0[2 * (J) + 1]); } else { e0_ = __builtin_amdgcn_exp2f(p1[2 * (J) - 16]); e1_ = __builtin_amdgcn_exp2f(p1[2 * (J) - 15]); } \
;                 sum += e0_; sum += e1_; asm volatile("" : "+v"(sum)); pkn[(J) >> 2][(J) & 3] = cvtpk_s(e0_, e1_); } while (0)
; __device__ __forceinline__ void attn_unit(LAS unsigned char* lds, bf16_t* Qm, const bf16_t* __restrict__ Kb, const bf16_t* __restrict__ Vt,
;                                           int b, int h, int qb, int lgS, float lam, float oscale, const float* __restrict__ subg, float* stash) {
;     ...
; #pragma unroll
;             for (int ks = 1; ks < 4; ++ks) {
; #pragma unroll
;                 for (int blk = 0; blk < 4; ++blk) {
;                     const int gi = (ks - 1) * 4 + blk;
;                     if (blk == 0 && ks < 3) {
; #pragma unroll
;                         for (int b2 = 0; b2 < 4; ++b2) { const bf16x8 v_ = *(const LAS bf16x8*)(lds + vs0 + vr + b2 * 32 * VP + (ks + 1) * 32); if (ks & 1) vfa[b2] = v_; else vfb[b2] = v_; }
;                     }
;                     o[blk] = __builtin_amdgcn_mfma_f32_32x32x16_bf16((ks & 1) ? vfb[blk] : vfa[blk], __builtin_bit_cast(bf16x8, pk[ks]), o[blk], 0, 0, 0);
;                     ATT_EXP2(gi);
;                     if (gi < 4) ATT_EXP2(12 + gi);
;                     ATT_SB();
;                 }
;             }
;     ...
;             lrun += sum;
; #pragma unroll
;             for (int j = 0; j < 4; ++j) pk[j] = pkn[j];
;             if (t + 2 < NT) ATT_KRD(kq2, 0, 1);
; #pragma unroll
;             for (int b2 = 0; b2 < 4; ++b2) vfa[b2] = *(const LAS bf16x8*)(lds + vs1 + vr + b2 * 32 * VP);
;             ATT_SB();
;             { const int tmp = vs0; vs0 = vs1; vs1 = vs2; vs2 = tmp; }
;             { const int tmp = kq0; kq0 = kq1; kq1 = kq2; kq2 = tmp; }
;             __syncthreads();
.LBB0_342:
	v_exp_f32_e32 v96, v96
	s_waitcnt lgkmcnt(3)
	v_mfma_f32_32x32x16_bf16 v[0:15], v[216:219], v[180:183], v[0:15]
	v_exp_f32_e32 v97, v97
	ds_read_b128 v[192:195], v251 offset:25408
	ds_read_b128 v[196:199], v251 offset:30016
	ds_read_b128 v[188:191], v251 offset:34624
	ds_read_b128 v[184:187], v251 offset:39232
	v_exp_f32_e32 v88, v88
	v_add_f32_e32 v200, 0, v96
	v_exp_f32_e32 v89, v89
	v_add_f32_e32 v200, v97, v200
	s_nop 0
	v_add_f32_e32 v200, v88, v200
	v_add_f32_e32 v200, v89, v200
	v_exp_f32_e32 v98, v98
	s_waitcnt lgkmcnt(6)
	v_mfma_f32_32x32x16_bf16 v[48:63], v[212:215], v[180:183], v[48:63]
	v_exp_f32_e32 v99, v99
	v_exp_f32_e32 v90, v90
	v_add_f32_e32 v200, v98, v200
	v_exp_f32_e32 v91, v91
	v_add_f32_e32 v200, v99, v200
	s_nop 0
	v_add_f32_e32 v200, v90, v200
	v_add_f32_e32 v200, v91, v200
	v_exp_f32_e32 v100, v100
	s_waitcnt lgkmcnt(5)
	v_mfma_f32_32x32x16_bf16 v[32:47], v[208:211], v[180:183], v[32:47]
	v_exp_f32_e32 v101, v101
	v_exp_f32_e32 v92, v92
	v_add_f32_e32 v200, v100, v200
	v_exp_f32_e32 v93, v93
	v_add_f32_e32 v200, v101, v200
	s_nop 0
	v_add_f32_e32 v200, v92, v200
	v_add_f32_e32 v200, v93, v200
	v_exp_f32_e32 v102, v102
	s_waitcnt lgkmcnt(4)
	v_mfma_f32_32x32x16_bf16 v[16:31], v[204:207], v[180:183], v[16:31]
	v_exp_f32_e32 v103, v103
	v_exp_f32_e32 v94, v94
	v_add_f32_e32 v180, v102, v200
	v_exp_f32_e32 v95, v95
	v_add_f32_e32 v180, v103, v180
	s_nop 0
	v_add_f32_e32 v180, v94, v180
	v_add_f32_e32 v212, v95, v180
	s_waitcnt lgkmcnt(3)
	v_mfma_f32_32x32x16_bf16 v[0:15], v[192:195], v[172:175], v[0:15]
	ds_read_b128 v[180:183], v251 offset:25440
	ds_read_b128 v[200:203], v251 offset:30048
	ds_read_b128 v[204:207], v251 offset:34656
	ds_read_b128 v[208:211], v251 offset:39264
	v_exp_f32_e32 v104, v104
	v_exp_f32_e32 v105, v105
	v_add_f32_e32 v156, v104, v212
	v_add_f32_e32 v156, v105, v156
	v_add_u32_e32 v251, s25, v220
	v_add_u32_e32 v160, s50, v235
	s_waitcnt lgkmcnt(6)
	v_mfma_f32_32x32x16_bf16 v[48:63], v[196:199], v[172:175], v[48:63]
	ds_read_b128 v[192:195], v251 offset:29952
	v_exp_f32_e32 v106, v106
	v_exp_f32_e32 v107, v107
	v_add_f32_e32 v156, v106, v156
	v_add_f32_e32 v156, v107, v156
	s_cmp_lg_u32 s98, 0
	s_cbranch_scc1 .Lmy_skip_m
	s_waitcnt lgkmcnt(1)
	s_barrier
.Lmy_skip_m:
	s_waitcnt lgkmcnt(6)
	v_mfma_f32_32x32x16_bf16 v[32:47], v[188:191], v[172:175], v[32:47]
	ds_read_b128 v[196:199], v251 offset:25344
	v_exp_f32_e32 v108, v108
	v_exp_f32_e32 v109, v109
	v_add_f32_e32 v156, v108, v156
	v_add_f32_e32 v156, v109, v156
	s_waitcnt lgkmcnt(6)
	v_mfma_f32_32x32x16_bf16 v[16:31], v[184:187], v[172:175], v[16:31]
	ds_read_b128 v[188:191], v251 offset:34560
	ds_read_b128 v[212:215], v160 offset:4224
	ds_read_b128 v[216:219], v160 offset:4736
	v_exp_f32_e32 v110, v110
	v_exp_f32_e32 v111, v111
	v_add_f32_e32 v156, v110, v156
	v_add_f32_e32 v156, v111, v156
	s_waitcnt lgkmcnt(8)
	v_mfma_f32_32x32x16_bf16 v[0:15], v[180:183], v[164:167], v[0:15]
	ds_read_b128 v[184:187], v251 offset:39168
	ds_read_b128 v[222:225], v160 offset:6336
	ds_read_b128 v[240:243], v160 offset:6848
	v_exp_f32_e32 v80, v80
	v_exp_f32_e32 v81, v81
	v_add_f32_e32 v156, v80, v156
	v_add_f32_e32 v156, v81, v156
	v_cvt_pk_bf16_f32 v180, v104, v105
	v_cvt_pk_bf16_f32 v181, v106, v107
	v_cvt_pk_bf16_f32 v182, v108, v109
	v_cvt_pk_bf16_f32 v183, v110, v111
	s_waitcnt lgkmcnt(10)
	v_mfma_f32_32x32x16_bf16 v[48:63], v[200:203], v[164:167], v[48:63]
	v_exp_f32_e32 v82, v82
	v_exp_f32_e32 v83, v83
	v_add_f32_e32 v156, v82, v156
	v_add_f32_e32 v156, v83, v156
	v_cvt_pk_bf16_f32 v200, v96, v97
	v_cvt_pk_bf16_f32 v201, v98, v99
	v_cvt_pk_bf16_f32 v202, v100, v101
	v_cvt_pk_bf16_f32 v203, v102, v103
	v_cvt_pk_bf16_f32 v172, v80, v81
	s_waitcnt lgkmcnt(9)
	v_mfma_f32_32x32x16_bf16 v[32:47], v[204:207], v[164:167], v[32:47]
	ds_read_b128 v[204:207], v160 offset:2112
	v_exp_f32_e32 v84, v84
	v_exp_f32_e32 v85, v85
	v_add_f32_e32 v156, v84, v156
	v_add_f32_e32 v156, v85, v156
	v_cvt_pk_bf16_f32 v173, v82, v83
	s_waitcnt lgkmcnt(9)
	v_mfma_f32_32x32x16_bf16 v[16:31], v[208:211], v[164:167], v[16:31]
	ds_read_b128 v[208:211], v160 offset:2624
	v_exp_f32_e32 v86, v86
	v_exp_f32_e32 v87, v87
	v_add_f32_e32 v156, v86, v156
	v_add_f32_e32 v156, v87, v156
	v_add_f32_e32 v249, v249, v156
	ds_read_b128 v[156:159], v160
	ds_read_b128 v[160:163], v160 offset:512
	v_cvt_pk_bf16_f32 v174, v84, v85
	v_cvt_pk_bf16_f32 v175, v86, v87
	v_cvt_pk_bf16_f32 v164, v88, v89
	v_cvt_pk_bf16_f32 v165, v90, v91
	v_cvt_pk_bf16_f32 v166, v92, v93
	v_cvt_pk_bf16_f32 v167, v94, v95
	s_add_i32 s57, s57, 1
	s_add_i32 s90, s90, 64
	s_mov_b64 s[28:29], 0x10000
	v_lshl_add_u64 v[238:239], v[238:239], 0, s[28:29]
	s_waitcnt lgkmcnt(0)
	s_cmp_eq_u32 s98, 0
	s_cbranch_scc1 .Lmy_skip_e
	s_barrier
